# mixer phases: flat_load replaced by global_load (addresses are global; keeps the loads out of lgkmcnt so LDS waits do not stall on them)
# speedup vs baseline: 1.0044x; 1.0017x over previous
.LBB0_1207:
	s_add_i32 s6, s11, 0xffffff80
	s_cmpk_lt_i32 s11, 0x80
	s_cselect_b32 s6, s11, s6
	s_cselect_b32 s7, 5, 2
	s_cselect_b32 s18, 16, 2
	s_cselect_b32 s19, 20, 2
	s_ashr_i32 s12, s6, s7
	s_lshl_b32 s6, s12, 11
	s_addk_i32 s6, 0x1000
	s_lshl_b32 s7, s12, 8
	s_cmpk_lt_i32 s11, 0x80
	s_cselect_b32 s6, s6, s7
	s_lshr_b32 s7, s11, 3
	s_cmpk_lt_i32 s11, 0x80
	s_cselect_b32 s7, s7, s11
	s_and_b32 s10, s7, 3
	s_min_i32 s7, s11, 0x80
	v_mov_b32_e32 v60, v176
	s_lshl_b32 s7, s7, 8
	s_and_b32 s7, s7, 0x700
	v_and_b32_e32 v61, 15, v60
	v_ashrrev_i32_e32 v4, 1, v60
	v_or_b32_e32 v5, s7, v61
	s_mul_i32 s7, s10, 0xc0
	v_bfe_u32 v62, v60, 4, 2
	v_and_b32_e32 v4, 0xffffffe0, v4
	s_add_u32 s8, s75, s7
	v_add3_u32 v92, v5, v4, s6
	s_addc_u32 s9, s66, 0
	v_lshlrev_b32_e32 v94, 4, v62
	v_mov_b32_e32 v95, v89
	v_lshl_add_u64 v[12:13], s[8:9], 0, v[94:95]
	v_or_b32_e32 v90, 16, v92
	v_mad_i64_i32 v[14:15], s[8:9], v92, s87, v[12:13]
	s_waitcnt vmcnt(0)
	v_mad_i64_i32 v[24:25], s[8:9], v90, s87, v[12:13]
	s_ashr_i32 s7, s6, 31
	s_lshl_b64 s[8:9], s[6:7], 10
	s_add_u32 s8, s81, s8
	s_addc_u32 s9, s84, s9
	s_lshl_b32 s44, s10, 7
	s_lshl_b32 s13, s10, 8
	v_ashrrev_i32_e32 v48, 3, v60
	s_add_u32 s8, s8, s13
	v_ashrrev_i32_e32 v49, 31, v48
	v_add_u32_e32 v52, 64, v48
	s_addc_u32 s9, s9, 0
	v_lshlrev_b64 v[50:51], 10, v[48:49]
	v_and_b32_e32 v63, 7, v60
	v_ashrrev_i32_e32 v53, 31, v52
	v_lshl_add_u64 v[28:29], s[8:9], 0, v[50:51]
	v_lshlrev_b32_e32 v96, 4, v63
	v_mov_b32_e32 v97, v89
	v_lshlrev_b64 v[54:55], 10, v[52:53]
	v_lshl_add_u64 v[32:33], v[28:29], 0, v[96:97]
	v_lshl_add_u64 v[28:29], s[8:9], 0, v[54:55]
	s_lshl_b64 s[10:11], s[6:7], 6
	v_lshl_add_u64 v[40:41], v[28:29], 0, v[96:97]
	v_ashrrev_i32_e32 v56, 2, v60
	global_load_dwordx4 v[4:7], v[14:15], off
	global_load_dwordx4 v[8:11], v[14:15], off offset:64
	s_nop 0
	global_load_dwordx4 v[12:15], v[14:15], off offset:128
	s_nop 0
	global_load_dwordx4 v[16:19], v[24:25], off
	global_load_dwordx4 v[20:23], v[24:25], off offset:64
	s_nop 0
	global_load_dwordx4 v[24:27], v[24:25], off offset:128
	s_waitcnt lgkmcnt(0)
	s_barrier
	s_add_u32 s10, s85, s10
	global_load_dwordx4 v[28:31], v[32:33], off
	s_nop 0
	global_load_dwordx4 v[32:35], v[32:33], off offset:128
	s_nop 0
	global_load_dwordx4 v[36:39], v[40:41], off
	s_nop 0
	global_load_dwordx4 v[40:43], v[40:41], off offset:128
	v_ashrrev_i32_e32 v57, 31, v56
	s_addc_u32 s11, s86, s11
	v_lshlrev_b64 v[58:59], 6, v[56:57]
	v_and_b32_e32 v64, 3, v60
	v_lshl_add_u64 v[44:45], s[10:11], 0, v[58:59]
	v_lshlrev_b32_e32 v98, 4, v64
	v_mov_b32_e32 v99, v89
	v_lshl_add_u64 v[44:45], v[44:45], 0, v[98:99]
	global_load_dwordx4 v[44:47], v[44:45], off
	v_mul_lo_u32 v95, v48, s88
	s_movk_i32 s8, 0xffd0
	v_mul_lo_u32 v65, v48, s8
	v_add_u32_e32 v66, v95, v96
	s_movk_i32 s8, 0x3400
	v_add_u32_e32 v68, v66, v65
	v_add3_u32 v65, v66, s8, v65
	s_or_b32 s8, s6, 0x80
	s_ashr_i32 s9, s8, 31
	s_lshl_b64 s[10:11], s[8:9], 10
	s_add_u32 s10, s81, s10
	s_addc_u32 s11, s84, s11
	s_add_u32 s10, s10, s13
	v_mul_lo_u32 v111, v56, s88
	s_addc_u32 s11, s11, 0
	v_add_u32_e32 v67, v111, v98
	s_lshl_b64 s[8:9], s[8:9], 6
	s_add_u32 s8, s85, s8
	s_addc_u32 s9, s86, s9
	v_lshlrev_b64 v[102:103], 9, v[48:49]
	v_mul_lo_u32 v185, v48, s95
	v_bfe_u32 v48, v60, 2, 2
	v_lshlrev_b64 v[104:105], 9, v[52:53]
	v_lshlrev_b32_e32 v52, 3, v64
	v_mov_b32_e32 v100, 0
	v_ashrrev_i32_e32 v93, 31, v92
	v_ashrrev_i32_e32 v91, 31, v90
	v_lshlrev_b64 v[106:107], 5, v[56:57]
	v_add_u32_e32 v186, 0x2800, v185
	s_waitcnt vmcnt(0) lgkmcnt(0)
	ds_write_b128 v66, v[28:31]
	ds_write_b128 v66, v[36:39] offset:13312
	ds_write_b128 v68, v[32:35] offset:26624
	ds_write_b128 v65, v[40:43] offset:23552
	ds_write_b128 v67, v[44:47] offset:128
	v_lshl_add_u64 v[28:29], s[10:11], 0, v[50:51]
	v_lshl_add_u64 v[32:33], v[28:29], 0, v[96:97]
	v_lshl_add_u64 v[28:29], s[10:11], 0, v[54:55]
	v_lshl_add_u64 v[40:41], v[28:29], 0, v[96:97]
	global_load_dwordx4 v[28:31], v[32:33], off
	s_nop 0
	global_load_dwordx4 v[32:35], v[32:33], off offset:128
	s_nop 0
	global_load_dwordx4 v[36:39], v[40:41], off
	s_nop 0
	global_load_dwordx4 v[40:43], v[40:41], off offset:128
	v_lshl_add_u64 v[44:45], s[8:9], 0, v[58:59]
	v_lshl_add_u64 v[44:45], v[44:45], 0, v[98:99]
	global_load_dwordx4 v[44:47], v[44:45], off
	v_lshlrev_b32_e32 v97, 2, v62
	v_or_b32_e32 v48, v97, v48
	v_lshlrev_b32_e32 v50, 3, v63
	v_mul_u32_u24_e32 v188, 0xa0, v48
	v_lshlrev_b32_e32 v48, 3, v60
	s_lshl_b32 s8, s12, 9
	v_add_u32_e32 v99, 0x3400, v95
	v_mul_u32_u24_e32 v187, 0xd0, v61
	v_and_b32_e32 v189, 24, v48
	s_ashr_i32 s9, s8, 31
	s_sub_i32 s20, 2, s18
	s_mov_b32 s10, 0
	v_mov_b32_e32 v190, 0xf149f2ca
	s_lshl_b32 s21, s44, 1
	v_lshlrev_b32_e32 v88, 1, v50
	v_lshlrev_b32_e32 v108, 1, v52
	v_mov_b32_e32 v81, 0xf149f2ca
	v_mov_b32_e32 v60, v0
	v_mov_b32_e32 v61, v0
	v_mov_b32_e32 v62, v0
	v_mov_b32_e32 v63, v0
	v_mov_b32_e32 v56, v0
	v_mov_b32_e32 v57, v0
	v_mov_b32_e32 v58, v0
	v_mov_b32_e32 v59, v0
	v_mov_b32_e32 v48, v0
	v_mov_b32_e32 v49, v0
	v_mov_b32_e32 v50, v0
	v_mov_b32_e32 v51, v0
	v_mov_b32_e32 v52, v0
	v_mov_b32_e32 v53, v0
	v_mov_b32_e32 v54, v0
	v_mov_b32_e32 v55, v0
	v_mov_b32_e32 v76, v0
	v_mov_b32_e32 v77, v0
	v_mov_b32_e32 v78, v0
	v_mov_b32_e32 v79, v0
	v_mov_b32_e32 v72, v0
	v_mov_b32_e32 v73, v0
	v_mov_b32_e32 v74, v0
	v_mov_b32_e32 v75, v0
	v_mov_b32_e32 v64, v0
	v_mov_b32_e32 v65, v0
	v_mov_b32_e32 v66, v0
	v_mov_b32_e32 v67, v0
	v_mov_b32_e32 v68, v0
	v_mov_b32_e32 v69, v0
	v_mov_b32_e32 v70, v0
	v_mov_b32_e32 v71, v0
	v_mov_b32_e32 v101, v100
	s_waitcnt lgkmcnt(0)
	s_barrier
	s_branch .LBB0_1211

.LBB0_1209:
	s_lshl_b32 s23, s23, 7
	s_add_u32 s16, s16, s23
	s_addc_u32 s17, s17, 0
	s_add_u32 s23, s42, s12
	s_addc_u32 s24, s43, s13
	s_lshl_b64 s[12:13], s[16:17], 10
	s_add_u32 s12, s23, s12
	s_addc_u32 s13, s24, s13
	s_add_u32 s12, s12, s21
	s_addc_u32 s13, s13, 0
	s_add_u32 s23, s42, s10
	s_addc_u32 s24, s43, s11
	s_lshl_b64 s[10:11], s[16:17], 6
	s_waitcnt vmcnt(0)
	v_lshl_add_u64 v[28:29], v[102:103], 1, s[12:13]
	s_add_u32 s10, s23, s10
	v_lshl_add_u64 v[32:33], v[28:29], 0, v[88:89]
	v_lshl_add_u64 v[28:29], v[104:105], 1, s[12:13]
	s_addc_u32 s11, s24, s11
	v_lshl_add_u64 v[40:41], v[28:29], 0, v[88:89]
	global_load_dwordx4 v[28:31], v[32:33], off
	s_nop 0
	global_load_dwordx4 v[32:35], v[32:33], off offset:128
	s_nop 0
	global_load_dwordx4 v[36:39], v[40:41], off
	s_nop 0
	global_load_dwordx4 v[40:43], v[40:41], off offset:128
	v_lshl_add_u64 v[44:45], v[106:107], 1, s[10:11]
	v_mov_b32_e32 v109, v89
	v_lshl_add_u64 v[44:45], v[44:45], 0, v[108:109]
	global_load_dwordx4 v[44:47], v[44:45], off

.LBB0_1225:
	s_lshl_b32 s8, s16, 11
	s_add_i32 s10, s8, 0x1000
	s_lshl_b32 s11, s16, 8
	s_and_b64 s[8:9], s[18:19], exec
	s_cselect_b32 s20, s10, s11
	s_lshl_b32 s8, s6, 2
	s_lshl_b32 s6, s7, 5
	s_add_i32 s9, s6, 0x200
	s_and_b64 s[6:7], s[18:19], exec
	s_cselect_b32 s17, s47, 0x100
	s_cselect_b32 s8, s9, s8
	s_cmp_eq_u32 s31, 0
	v_ashrrev_i32_e32 v50, 3, v49
	s_cselect_b64 s[6:7], -1, 0
	s_ashr_i32 s9, s8, 31
	s_lshl_b64 s[22:23], s[8:9], 13
	s_waitcnt vmcnt(0)
	v_lshlrev_b32_e32 v44, 6, v50
	s_add_u32 s10, s67, s22
	v_ashrrev_i32_e32 v45, 31, v44
	s_addc_u32 s11, s64, s23
	v_lshlrev_b64 v[28:29], 1, v[44:45]
	v_lshl_add_u64 v[20:21], s[10:11], 0, v[28:29]
	s_add_u32 s10, s65, s22
	s_addc_u32 s11, s54, s23
	v_lshl_add_u64 v[22:23], s[10:11], 0, v[28:29]
	s_add_u32 s10, s55, s22
	v_xad_u32 v36, v50, -1, s17
	s_addc_u32 s11, s61, s23
	v_lshl_add_u64 v[28:29], s[10:11], 0, v[28:29]
	s_add_u32 s10, s62, s22
	v_lshlrev_b32_e32 v46, 3, v49
	v_cndmask_b32_e64 v36, v36, v50, s[6:7]
	s_addc_u32 s11, s63, s23
	v_ashrrev_i32_e32 v47, 31, v46
	s_ashr_i32 s21, s20, 31
	v_ashrrev_i32_e32 v37, 31, v36
	s_lshl_b32 s44, s29, 7
	s_lshl_b64 s[24:25], s[8:9], 8
	v_lshl_add_u64 v[32:33], v[46:47], 1, s[10:11]
	v_lshl_add_u64 v[36:37], v[36:37], 0, s[20:21]
	s_add_u32 s10, s46, s24
	v_lshlrev_b64 v[36:37], 9, v[36:37]
	s_addc_u32 s11, s76, s25
	s_lshl_b64 s[26:27], s[8:9], 2
	v_and_b32_e32 v51, 7, v49
	v_lshl_add_u64 v[36:37], s[50:51], 0, v[36:37]
	v_lshlrev_b32_e32 v64, 4, v49
	s_add_u32 s8, s77, s26
	v_lshlrev_b32_e32 v88, 4, v51
	v_lshl_add_u64 v[36:37], v[36:37], 0, s[44:45]
	v_and_b32_e32 v38, 0xf0, v64
	v_mov_b32_e32 v39, v89
	s_addc_u32 s9, s38, s27
	v_lshl_add_u64 v[20:21], v[20:21], 0, v[88:89]
	v_lshl_add_u64 v[24:25], v[22:23], 0, v[88:89]
	v_lshl_add_u64 v[28:29], v[28:29], 0, v[88:89]
	v_lshl_add_u64 v[36:37], v[36:37], 0, v[88:89]
	v_lshl_add_u64 v[40:41], s[10:11], 0, v[38:39]
	v_mov_b64_e32 v[52:53], s[8:9]
	s_barrier
	global_load_dwordx4 v[20:23], v[20:21], off
	s_nop 0
	global_load_dwordx4 v[24:27], v[24:25], off
	s_nop 0
	global_load_dwordx4 v[28:31], v[28:29], off
	s_nop 0
	global_load_dwordx4 v[32:35], v[32:33], off
	s_nop 0
	global_load_dwordx4 v[36:39], v[36:37], off
	s_nop 0
	global_load_dwordx4 v[40:43], v[40:41], off
	v_mul_lo_u32 v65, v50, s97
	global_load_dword v66, v[52:53], off
	v_add_u32_e32 v52, v65, v88
	v_cmp_gt_i32_e64 s[8:9], 16, v49
	s_waitcnt vmcnt(0) lgkmcnt(0)
	ds_write_b128 v52, v[20:23]
	ds_write_b128 v52, v[24:27] offset:18432
	ds_write_b128 v52, v[28:31] offset:27648
	ds_write_b128 v52, v[36:39] offset:9216
	ds_write_b128 v64, v[32:35] offset:36864
	s_and_saveexec_b64 s[10:11], s[8:9]
	ds_write_b128 v64, v[40:43] offset:45056
	s_or_b64 exec, exec, s[10:11]
	v_cmp_eq_u32_e64 s[10:11], 16, v49
	s_and_saveexec_b64 s[12:13], s[10:11]
	ds_write_b32 v89, v66 offset:45312
	s_or_b64 exec, exec, s[12:13]
	s_lshr_b32 s33, s30, 6
	s_lshl_b32 s36, s29, 6
	s_and_b64 s[12:13], s[6:7], exec
	s_mov_b32 s12, 0x6952000
	s_cselect_b32 s12, s12, 0x6f52000
	s_add_u32 s40, s42, s12
	s_addc_u32 s41, s43, 0
	s_ashr_i32 s44, s30, 8
	s_and_b64 s[12:13], s[18:19], exec
	s_cselect_b32 s35, 32, 4
	s_lshl_b32 s36, s36, 1
	v_lshlrev_b32_e32 v52, 3, v51
	s_add_u32 s12, s50, s36
	s_addc_u32 s13, s51, 0
	v_lshlrev_b32_e32 v52, 1, v52
	v_mov_b32_e32 v53, v89
	v_lshl_add_u64 v[52:53], s[12:13], 0, v[52:53]
	s_lshl_b32 s12, s37, 1
	s_add_i32 s13, s12, s44
	s_sub_i32 s12, s12, s44
	s_lshl_b32 s13, s13, 10
	s_lshl_b32 s12, s12, 6
	s_lshl_b32 s72, s44, 1
	s_add_i32 s73, s13, 0x16400
	s_add_i32 s12, s12, 64
	v_and_b32_e32 v56, 63, v49
	s_cmpk_lt_u32 s30, 0x100
	v_and_b32_e32 v67, 48, v49
	v_or_b32_e32 v49, s12, v56
	s_cselect_b64 s[12:13], -1, 0
	s_lshl_b32 s74, s44, 5
	s_add_u32 s36, s40, s36
	s_addc_u32 s41, s41, 0
	s_lshl_b32 s40, s37, 5
	s_add_u32 s40, s36, s40
	v_lshlrev_b32_e32 v68, 3, v48
	v_lshlrev_b32_e32 v80, 4, v49
	v_lshlrev_b32_e32 v58, 2, v48
	s_addc_u32 s41, s41, 0
	v_lshlrev_b32_e32 v48, 1, v62
	v_mov_b32_e32 v49, v89
	v_lshl_add_u64 v[54:55], s[40:41], 0, v[48:49]
	s_or_b32 s41, s72, 1
	s_lshl_b32 s36, s44, 10
	s_lshl_b32 s37, s37, 11
	s_lshl_b32 s40, s41, 9
	v_lshl_or_b32 v48, s41, 4, v62
	s_add_u32 s26, s26, 0xfc52004
	v_mul_lo_u32 v71, v48, s97
	v_sub_u32_e32 v48, s17, v58
	s_addc_u32 s27, s27, 0
	v_subrev_u32_e32 v48, s74, v48
	s_add_u32 s24, s24, 0xfbf2100
	v_or_b32_e32 v57, s74, v62
	v_subrev_u32_e32 v76, 17, v48
	s_addc_u32 s25, s25, 0
	v_lshlrev_b32_e32 v48, 4, v62
	v_lshlrev_b32_e32 v79, 4, v56
	v_lshlrev_b32_e32 v69, 3, v56
	v_mul_lo_u32 v70, v57, s97
	v_lshl_add_u64 v[56:57], s[24:25], 0, v[48:49]
	s_add_u32 s24, s22, 0x7b54000
	s_addc_u32 s25, s23, 0
	v_or_b32_e32 v73, s74, v58
	v_lshl_add_u64 v[58:59], v[46:47], 1, s[24:25]
	v_lshl_or_b32 v46, v51, 4, s22
	v_mov_b32_e32 v47, s23
	v_lshlrev_b32_e32 v74, 2, v73
	v_lshl_add_u64 v[60:61], v[44:45], 1, v[46:47]
	v_sub_u32_e32 v44, s17, v50
	s_mov_b32 s34, 0
	v_mul_u32_u24_e32 v72, 0x90, v62
	v_or_b32_e32 v75, 64, v74
	v_add_u32_e32 v77, 64, v50
	v_add_u32_e32 v78, 0xffffffbf, v44
	v_add_u32_e32 v79, s73, v79
	v_add_u32_e32 v80, 0x16400, v80
	s_mov_b32 s25, 0
	s_waitcnt lgkmcnt(0)
	s_barrier
	s_branch .LBB0_1232

.LBB0_1232:
	s_add_i32 s24, s25, 1
	s_cmp_lt_u32 s24, s35
	s_cselect_b64 s[22:23], -1, 0
	s_cmp_ge_u32 s24, s35
	s_cbranch_scc1 .LBB0_1234
	s_waitcnt vmcnt(0)
	v_lshl_add_u64 v[28:29], s[42:43], 0, v[60:61]
	v_add_co_u32_e32 v20, vcc, 0x8754000, v28
	v_add_u32_e32 v36, s34, v77
	s_nop 0
	v_addc_co_u32_e32 v21, vcc, 0, v29, vcc
	v_cndmask_b32_e64 v36, v78, v36, s[6:7]
	v_add_co_u32_e32 v24, vcc, 0xe3f4000, v28
	v_ashrrev_i32_e32 v37, 31, v36
	s_nop 0
	v_addc_co_u32_e32 v25, vcc, 0, v29, vcc
	v_lshl_add_u64 v[36:37], v[36:37], 0, s[20:21]
	s_add_u32 s72, s42, s26
	v_add_co_u32_e32 v28, vcc, 0xeff4000, v28
	v_lshlrev_b64 v[36:37], 9, v[36:37]
	s_addc_u32 s73, s43, s27
	v_addc_co_u32_e32 v29, vcc, 0, v29, vcc
	v_lshl_add_u64 v[32:33], s[42:43], 0, v[58:59]
	v_lshl_add_u64 v[36:37], v[52:53], 0, v[36:37]
	v_lshl_add_u64 v[40:41], s[42:43], 0, v[56:57]
	v_mov_b64_e32 v[44:45], s[72:73]
	global_load_dwordx4 v[20:23], v[20:21], off
	s_nop 0
	global_load_dwordx4 v[24:27], v[24:25], off
	s_nop 0
	global_load_dwordx4 v[28:31], v[28:29], off
	s_nop 0
	global_load_dwordx4 v[32:35], v[32:33], off
	s_nop 0
	global_load_dwordx4 v[36:39], v[36:37], off
	s_nop 0
	global_load_dwordx4 v[40:43], v[40:41], off
	s_nop 0
	global_load_dword v66, v[44:45], off

.Lqe2:
	s_add_i32 s8, s10, s91
	s_min_i32 s6, s8, 0x80
	s_lshl_b32 s6, s6, 8
	s_and_b32 s12, s6, 0x700
	s_min_u32 s6, s12, 0x680
	s_add_i32 s9, s8, 0xffffff80
	s_add_i32 s11, s6, 0x180
	s_cmpk_lt_i32 s8, 0x80
	s_cselect_b64 s[6:7], -1, 0
	s_and_b64 s[6:7], s[6:7], exec
	v_sub_u32_e64 v4, s12, v181 clamp
	s_cselect_b32 s6, s8, s9
	s_cselect_b32 s7, 5, 2
	v_readfirstlane_b32 s9, v4
	s_cselect_b32 s13, s9, 0
	s_cselect_b32 s9, s11, 0x100
	s_ashr_i32 s14, s6, s7
	s_lshl_b32 s6, s14, 11
	s_add_i32 s11, s6, 0x1000
	s_lshl_b32 s15, s14, 8
	s_cmpk_lt_i32 s8, 0x80
	s_cselect_b64 s[6:7], -1, 0
	s_and_b64 s[6:7], s[6:7], exec
	s_cselect_b32 s15, s11, s15
	s_lshr_b32 s11, s10, 3
	s_cmpk_lt_i32 s8, 0x80
	s_cselect_b64 s[72:73], -1, 0
	s_waitcnt vmcnt(0)
	v_mov_b32_e32 v20, v176
	s_and_b64 s[6:7], s[72:73], exec
	s_cselect_b32 s6, s11, s10
	v_ashrrev_i32_e32 v4, 1, v20
	s_and_b32 s17, s6, 3
	v_and_b32_e32 v40, 0xffffffe0, v4
	v_and_b32_e32 v38, 15, v20
	v_add_u32_e32 v4, s12, v40
	s_lshl_b32 s6, s17, 7
	v_bfe_u32 v39, v20, 4, 2
	v_or_b32_e32 v4, v4, v38
	s_add_u32 s6, s78, s6
	v_add_u32_e32 v92, s15, v4
	s_addc_u32 s7, s57, 0
	v_lshlrev_b32_e32 v94, 4, v39
	v_mov_b32_e32 v95, v89
	v_lshl_add_u64 v[12:13], s[6:7], 0, v[94:95]
	v_ashrrev_i32_e32 v93, 31, v92
	s_mov_b64 s[6:7], s[0:1]
	v_lshlrev_b64 v[4:5], 9, v[92:93]
	s_add_u32 s6, s6, s79
	v_lshl_add_u64 v[8:9], v[12:13], 0, v[4:5]
	s_addc_u32 s7, s7, s89
	global_load_dwordx4 v[4:7], v[8:9], off
	s_nop 0
	global_load_dwordx4 v[8:11], v[8:9], off offset:64
	s_load_dwordx2 s[6:7], s[6:7], 0x98
	v_or_b32_e32 v90, 16, v92
	v_ashrrev_i32_e32 v91, 31, v90
	v_lshlrev_b64 v[14:15], 9, v[90:91]
	s_lshl_b32 s8, s17, 2
	v_lshl_add_u64 v[16:17], v[12:13], 0, v[14:15]
	v_mov_b32_e32 v21, s8
	global_load_dwordx4 v[12:15], v[16:17], off
	s_nop 0
	global_load_dwordx4 v[16:19], v[16:17], off offset:64
	s_sub_i32 s16, s9, s13
	s_waitcnt lgkmcnt(0)
	global_load_dword v41, v21, s[6:7]
	s_ashr_i32 s92, s16, 7
	s_cmp_lt_i32 s92, 1
	s_mov_b64 s[8:9], -1
	s_barrier
	s_cbranch_scc0 .LBB0_1287
	s_lshl_b32 s6, s14, 9
	s_ashr_i32 s7, s6, 31
	s_sub_i32 s8, 0, s16
	s_add_u32 s6, s8, s6
	s_addc_u32 s7, 0, s7
	s_mov_b64 s[8:9], 0

.LBB0_1290:
	s_and_b64 s[18:19], s[72:73], exec
	s_cselect_b32 s18, 4, 0
	s_add_i32 s44, s92, s18
	s_add_u32 s10, s42, s10
	s_addc_u32 s11, s43, s11
	s_lshl_b64 s[6:7], s[6:7], 8
	s_add_u32 s10, s10, s6
	s_addc_u32 s11, s11, s7
	s_lshl_b32 s18, s17, 5
	s_and_b32 s18, s18, 64
	s_lshl_b32 s93, s18, 1
	s_add_u32 s10, s10, s93
	s_addc_u32 s11, s11, 0
	s_add_u32 s8, s42, s8
	s_addc_u32 s9, s43, s9
	s_add_u32 s6, s8, s6
	v_ashrrev_i32_e32 v36, 3, v20
	s_addc_u32 s7, s9, s7
	v_ashrrev_i32_e32 v37, 31, v36
	v_add_u32_e32 v42, 64, v36
	s_add_u32 s6, s6, s93
	v_lshlrev_b64 v[28:29], 8, v[36:37]
	v_and_b32_e32 v44, 7, v20
	v_ashrrev_i32_e32 v43, 31, v42
	s_addc_u32 s7, s7, 0
	v_lshl_add_u64 v[22:23], s[10:11], 0, v[28:29]
	v_lshlrev_b32_e32 v98, 4, v44
	v_mov_b32_e32 v99, v89
	v_lshlrev_b64 v[30:31], 8, v[42:43]
	v_lshl_add_u64 v[20:21], v[22:23], 0, v[98:99]
	v_lshl_add_u64 v[22:23], s[10:11], 0, v[30:31]
	v_lshl_add_u64 v[28:29], s[6:7], 0, v[28:29]
	v_lshl_add_u64 v[30:31], s[6:7], 0, v[30:31]
	v_lshl_add_u64 v[24:25], v[22:23], 0, v[98:99]
	v_lshl_add_u64 v[28:29], v[28:29], 0, v[98:99]
	v_lshl_add_u64 v[32:33], v[30:31], 0, v[98:99]
	global_load_dwordx4 v[20:23], v[20:21], off
	s_nop 0
	global_load_dwordx4 v[24:27], v[24:25], off
	s_nop 0
	global_load_dwordx4 v[28:31], v[28:29], off
	s_nop 0
	global_load_dwordx4 v[32:35], v[32:33], off
	v_mul_lo_u32 v99, v36, s97
	v_lshlrev_b32_e32 v95, 3, v44
	v_lshlrev_b64 v[100:101], 7, v[36:37]
	v_add_u32_e32 v37, v99, v98
	v_lshlrev_b32_e32 v44, 4, v42
	v_lshlrev_b64 v[104:105], 7, v[42:43]
	s_movk_i32 s6, 0x2400
	s_cmp_lt_i32 s44, 2
	v_lshl_add_u32 v42, v36, 4, v37
	v_add3_u32 v43, v37, s6, v44
	s_waitcnt vmcnt(0) lgkmcnt(0)
	ds_write_b128 v37, v[20:23]
	ds_write_b128 v37, v[24:27] offset:9216
	ds_write_b128 v42, v[28:31] offset:18432
	ds_write_b128 v43, v[32:35] offset:18432
	s_cbranch_scc1 .LBB0_1297
	s_cmp_lt_i32 s92, 2
	s_mov_b64 s[8:9], -1
	s_cbranch_scc0 .LBB0_1293
	s_lshl_b32 s6, s14, 9
	s_ashr_i32 s7, s6, 31
	s_sub_i32 s8, 0x80, s16
	s_add_u32 s6, s8, s6
	s_addc_u32 s7, 0, s7
	s_mov_b64 s[8:9], 0

.LBB0_1296:
	s_add_u32 s10, s42, s10
	s_addc_u32 s11, s43, s11
	s_lshl_b64 s[6:7], s[6:7], 8
	s_add_u32 s10, s10, s6
	s_addc_u32 s11, s11, s7
	s_add_u32 s10, s10, s93
	s_addc_u32 s11, s11, 0
	s_add_u32 s8, s42, s8
	s_addc_u32 s9, s43, s9
	s_add_u32 s6, s8, s6
	s_addc_u32 s7, s9, s7
	s_add_u32 s6, s6, s93
	s_addc_u32 s7, s7, 0
	v_lshlrev_b64 v[28:29], 1, v[100:101]
	v_lshlrev_b64 v[30:31], 1, v[104:105]
	v_lshl_add_u64 v[20:21], s[10:11], 0, v[28:29]
	v_lshlrev_b32_e32 v88, 1, v95
	v_lshl_add_u64 v[22:23], s[10:11], 0, v[30:31]
	v_lshl_add_u64 v[28:29], s[6:7], 0, v[28:29]
	v_lshl_add_u64 v[30:31], s[6:7], 0, v[30:31]
	v_lshl_add_u64 v[20:21], v[20:21], 0, v[88:89]
	v_lshl_add_u64 v[24:25], v[22:23], 0, v[88:89]
	v_lshl_add_u64 v[28:29], v[28:29], 0, v[88:89]
	v_lshl_add_u64 v[32:33], v[30:31], 0, v[88:89]
	global_load_dwordx4 v[20:23], v[20:21], off
	s_nop 0
	global_load_dwordx4 v[24:27], v[24:25], off
	s_nop 0
	global_load_dwordx4 v[28:31], v[28:29], off
	s_nop 0
	global_load_dwordx4 v[32:35], v[32:33], off

.LBB0_1307:
	s_add_u32 s10, s42, s10
	s_addc_u32 s11, s43, s11
	s_lshl_b64 s[8:9], s[8:9], 8
	s_add_u32 s10, s10, s8
	s_addc_u32 s11, s11, s9
	s_add_u32 s10, s10, s93
	s_addc_u32 s11, s11, 0
	s_add_u32 s6, s42, s6
	s_addc_u32 s7, s43, s7
	s_add_u32 s6, s6, s8
	s_addc_u32 s7, s7, s9
	s_add_u32 s6, s6, s93
	s_addc_u32 s7, s7, 0
	s_waitcnt vmcnt(0)
	v_lshlrev_b64 v[28:29], 1, v[100:101]
	v_lshlrev_b64 v[30:31], 1, v[104:105]
	v_lshl_add_u64 v[20:21], s[10:11], 0, v[28:29]
	v_lshlrev_b32_e32 v88, 1, v95
	v_lshl_add_u64 v[22:23], s[10:11], 0, v[30:31]
	v_lshl_add_u64 v[28:29], s[6:7], 0, v[28:29]
	v_lshl_add_u64 v[30:31], s[6:7], 0, v[30:31]
	v_lshl_add_u64 v[20:21], v[20:21], 0, v[88:89]
	v_lshl_add_u64 v[24:25], v[22:23], 0, v[88:89]
	v_lshl_add_u64 v[28:29], v[28:29], 0, v[88:89]
	v_lshl_add_u64 v[32:33], v[30:31], 0, v[88:89]
	global_load_dwordx4 v[20:23], v[20:21], off
	s_nop 0
	global_load_dwordx4 v[24:27], v[24:25], off
	s_nop 0
	global_load_dwordx4 v[28:31], v[28:29], off
	s_nop 0
	global_load_dwordx4 v[32:35], v[32:33], off

.Lhy_ctx0_done:
	s_and_b64 s[18:19], s[6:7], exec
	s_cselect_b32 s44, s82, 0xddf2000
	v_lshl_add_u64 v[20:21], v[12:13], 0, s[44:45]
	v_lshl_add_u64 v[18:19], s[8:9], 1, v[20:21]
	global_load_dwordx2 v[32:33], v[18:19], off
	v_cndmask_b32_e64 v18, v23, v22, s[6:7]
	s_lshl_b32 s6, s14, 1
	s_add_i32 s6, s16, s6
	v_mov_b32_e32 v34, v8
	v_lshl_add_u32 v8, v25, 1, s6
	ds_read_b64 v[36:37], v8 offset:512
	v_mov_b32_e32 v35, v10
	v_mov_b32_e32 v10, v9
	s_mov_b64 s[6:7], -1
	s_and_b64 vcc, exec, s[12:13]
	s_waitcnt lgkmcnt(0)
	v_lshlrev_b32_e32 v9, 16, v37
	v_lshlrev_b32_e32 v8, 16, v36
	v_and_b32_e32 v37, 0xffff0000, v37
	v_and_b32_e32 v36, 0xffff0000, v36
	v_pk_fma_f32 v[8:9], v[18:19], v[8:9], v[34:35] op_sel_hi:[0,1,1]
	v_pk_fma_f32 v[10:11], v[18:19], v[36:37], v[10:11] op_sel_hi:[0,1,1]
	s_waitcnt vmcnt(0)
	v_lshlrev_b32_e32 v35, 16, v33
	v_lshlrev_b32_e32 v34, 16, v32
	v_and_b32_e32 v33, 0xffff0000, v33
	v_and_b32_e32 v32, 0xffff0000, v32
	v_pk_mul_f32 v[10:11], v[10:11], v[32:33]
	v_pk_mul_f32 v[8:9], v[8:9], v[34:35]
	v_and_b32_sdwa v32, v11, v177 dst_sel:DWORD dst_unused:UNUSED_PAD src0_sel:WORD_1 src1_sel:DWORD
	v_and_b32_sdwa v33, v10, v177 dst_sel:DWORD dst_unused:UNUSED_PAD src0_sel:WORD_1 src1_sel:DWORD
	v_and_b32_sdwa v19, v9, v177 dst_sel:DWORD dst_unused:UNUSED_PAD src0_sel:WORD_1 src1_sel:DWORD
	v_and_b32_sdwa v31, v8, v177 dst_sel:DWORD dst_unused:UNUSED_PAD src0_sel:WORD_1 src1_sel:DWORD
	v_add3_u32 v11, v11, v32, s60
	v_add3_u32 v10, v10, v33, s60
	v_add3_u32 v8, v8, v31, s60
	v_add3_u32 v9, v9, v19, s60
	v_and_b32_e32 v11, 0xffff0000, v11
	v_and_b32_e32 v10, 0xffff0000, v10
	v_or_b32_sdwa v9, v11, v9 dst_sel:DWORD dst_unused:UNUSED_PAD src0_sel:DWORD src1_sel:WORD_1
	v_or_b32_sdwa v8, v10, v8 dst_sel:DWORD dst_unused:UNUSED_PAD src0_sel:DWORD src1_sel:WORD_1
	s_cbranch_vccz .LBB0_1339
	flat_store_dwordx2 v[14:15], v[8:9]
	s_mov_b64 s[6:7], 0

.LBB0_1341:
	v_lshl_add_u64 v[8:9], s[10:11], 1, v[20:21]
	global_load_dwordx2 v[8:9], v[8:9], off
	s_lshl_b32 s6, s15, 1
	s_add_i32 s16, s16, s6
	v_mov_b32_e32 v10, v4
	v_lshl_add_u32 v4, v25, 1, s16
	ds_read_b64 v[20:21], v4 offset:512
	v_cndmask_b32_e64 v4, 0, 1, s[12:13]
	v_mov_b32_e32 v19, v18
	v_mov_b32_e32 v11, v6
	v_mov_b32_e32 v6, v5
	v_cmp_ne_u32_e64 s[6:7], 1, v4
	s_waitcnt lgkmcnt(0)
	v_lshlrev_b32_e32 v5, 16, v21
	v_lshlrev_b32_e32 v4, 16, v20
	v_and_b32_e32 v21, 0xffff0000, v21
	v_and_b32_e32 v20, 0xffff0000, v20
	v_pk_fma_f32 v[4:5], v[18:19], v[4:5], v[10:11]
	v_pk_fma_f32 v[6:7], v[18:19], v[20:21], v[6:7]
	s_andn2_b64 vcc, exec, s[12:13]
	s_mov_b64 s[12:13], -1
	s_waitcnt vmcnt(0)
	v_lshlrev_b32_e32 v11, 16, v9
	v_lshlrev_b32_e32 v10, 16, v8
	v_and_b32_e32 v9, 0xffff0000, v9
	v_and_b32_e32 v8, 0xffff0000, v8
	v_pk_mul_f32 v[6:7], v[6:7], v[8:9]
	v_pk_mul_f32 v[4:5], v[4:5], v[10:11]
	v_and_b32_sdwa v10, v7, v177 dst_sel:DWORD dst_unused:UNUSED_PAD src0_sel:WORD_1 src1_sel:DWORD
	v_and_b32_sdwa v11, v6, v177 dst_sel:DWORD dst_unused:UNUSED_PAD src0_sel:WORD_1 src1_sel:DWORD
	v_and_b32_sdwa v8, v5, v177 dst_sel:DWORD dst_unused:UNUSED_PAD src0_sel:WORD_1 src1_sel:DWORD
	v_and_b32_sdwa v9, v4, v177 dst_sel:DWORD dst_unused:UNUSED_PAD src0_sel:WORD_1 src1_sel:DWORD
	v_add3_u32 v7, v7, v10, s60
	v_add3_u32 v6, v6, v11, s60
	v_add3_u32 v4, v4, v9, s60
	v_add3_u32 v5, v5, v8, s60
	v_and_b32_e32 v7, 0xffff0000, v7
	v_and_b32_e32 v6, 0xffff0000, v6
	v_or_b32_sdwa v5, v7, v5 dst_sel:DWORD dst_unused:UNUSED_PAD src0_sel:DWORD src1_sel:WORD_1
	v_or_b32_sdwa v4, v6, v4 dst_sel:DWORD dst_unused:UNUSED_PAD src0_sel:DWORD src1_sel:WORD_1
	s_cbranch_vccnz .LBB0_1343
	s_mov_b64 s[12:13], 0
	flat_store_dwordx2 v[16:17], v[4:5]

.LBB0_2964:
	s_add_i32 s6, s11, 0xffffff80
	s_cmpk_lt_i32 s11, 0x80
	s_cselect_b32 s6, s11, s6
	s_cselect_b32 s7, 5, 2
	s_cselect_b32 s18, 16, 2
	s_cselect_b32 s19, 20, 2
	s_ashr_i32 s12, s6, s7
	s_lshl_b32 s6, s12, 11
	s_addk_i32 s6, 0x1000
	s_lshl_b32 s7, s12, 8
	s_cmpk_lt_i32 s11, 0x80
	s_cselect_b32 s6, s6, s7
	s_lshr_b32 s7, s11, 3
	s_cmpk_lt_i32 s11, 0x80
	s_cselect_b32 s7, s7, s11
	s_and_b32 s10, s7, 3
	s_min_i32 s7, s11, 0x80
	v_mov_b32_e32 v60, v175
	s_lshl_b32 s7, s7, 8
	s_and_b32 s7, s7, 0x700
	v_and_b32_e32 v61, 15, v60
	v_ashrrev_i32_e32 v4, 1, v60
	v_or_b32_e32 v5, s7, v61
	s_mul_i32 s7, s10, 0xc0
	v_bfe_u32 v62, v60, 4, 2
	v_and_b32_e32 v4, 0xffffffe0, v4
	s_add_u32 s8, s74, s7
	v_add3_u32 v92, v5, v4, s6
	s_addc_u32 s9, s75, 0
	v_lshlrev_b32_e32 v94, 4, v62
	v_mov_b32_e32 v95, v89
	v_lshl_add_u64 v[12:13], s[8:9], 0, v[94:95]
	v_or_b32_e32 v90, 16, v92
	v_mad_i64_i32 v[14:15], s[8:9], v92, s59, v[12:13]
	s_waitcnt vmcnt(0)
	v_mad_i64_i32 v[24:25], s[8:9], v90, s59, v[12:13]
	s_ashr_i32 s7, s6, 31
	s_lshl_b64 s[8:9], s[6:7], 10
	s_add_u32 s8, s55, s8
	s_addc_u32 s9, s60, s9
	s_lshl_b32 s44, s10, 7
	s_lshl_b32 s13, s10, 8
	v_ashrrev_i32_e32 v48, 3, v60
	s_add_u32 s8, s8, s13
	v_ashrrev_i32_e32 v49, 31, v48
	v_add_u32_e32 v52, 64, v48
	s_addc_u32 s9, s9, 0
	v_lshlrev_b64 v[50:51], 10, v[48:49]
	v_and_b32_e32 v63, 7, v60
	v_ashrrev_i32_e32 v53, 31, v52
	v_lshl_add_u64 v[28:29], s[8:9], 0, v[50:51]
	v_lshlrev_b32_e32 v96, 4, v63
	v_mov_b32_e32 v97, v89
	v_lshlrev_b64 v[54:55], 10, v[52:53]
	v_lshl_add_u64 v[32:33], v[28:29], 0, v[96:97]
	v_lshl_add_u64 v[28:29], s[8:9], 0, v[54:55]
	s_lshl_b64 s[10:11], s[6:7], 6
	v_lshl_add_u64 v[40:41], v[28:29], 0, v[96:97]
	v_ashrrev_i32_e32 v56, 2, v60
	global_load_dwordx4 v[4:7], v[14:15], off
	global_load_dwordx4 v[8:11], v[14:15], off offset:64
	s_nop 0
	global_load_dwordx4 v[12:15], v[14:15], off offset:128
	s_nop 0
	global_load_dwordx4 v[16:19], v[24:25], off
	global_load_dwordx4 v[20:23], v[24:25], off offset:64
	s_nop 0
	global_load_dwordx4 v[24:27], v[24:25], off offset:128
	s_waitcnt lgkmcnt(0)
	s_barrier
	s_add_u32 s10, s61, s10
	global_load_dwordx4 v[28:31], v[32:33], off
	s_nop 0
	global_load_dwordx4 v[32:35], v[32:33], off offset:128
	s_nop 0
	global_load_dwordx4 v[36:39], v[40:41], off
	s_nop 0
	global_load_dwordx4 v[40:43], v[40:41], off offset:128
	v_ashrrev_i32_e32 v57, 31, v56
	s_addc_u32 s11, s62, s11
	v_lshlrev_b64 v[58:59], 6, v[56:57]
	v_and_b32_e32 v64, 3, v60
	v_lshl_add_u64 v[44:45], s[10:11], 0, v[58:59]
	v_lshlrev_b32_e32 v98, 4, v64
	v_mov_b32_e32 v99, v89
	v_lshl_add_u64 v[44:45], v[44:45], 0, v[98:99]
	global_load_dwordx4 v[44:47], v[44:45], off
	v_mul_lo_u32 v95, v48, s90
	s_movk_i32 s8, 0xffd0
	v_mul_lo_u32 v65, v48, s8
	v_add_u32_e32 v66, v95, v96
	s_movk_i32 s8, 0x3400
	v_add_u32_e32 v68, v66, v65
	v_add3_u32 v65, v66, s8, v65
	s_or_b32 s8, s6, 0x80
	s_ashr_i32 s9, s8, 31
	s_lshl_b64 s[10:11], s[8:9], 10
	s_add_u32 s10, s55, s10
	s_addc_u32 s11, s60, s11
	s_add_u32 s10, s10, s13
	v_mul_lo_u32 v111, v56, s90
	s_addc_u32 s11, s11, 0
	v_add_u32_e32 v67, v111, v98
	s_lshl_b64 s[8:9], s[8:9], 6
	s_add_u32 s8, s61, s8
	s_addc_u32 s9, s62, s9
	v_lshlrev_b64 v[102:103], 9, v[48:49]
	v_lshlrev_b64 v[104:105], 9, v[52:53]
	v_lshlrev_b32_e32 v52, 3, v64
	v_mov_b32_e32 v100, 0
	v_ashrrev_i32_e32 v93, 31, v92
	v_ashrrev_i32_e32 v91, 31, v90
	v_lshlrev_b64 v[106:107], 5, v[56:57]
	v_mul_u32_u24_e32 v186, 0xd0, v61
	v_mov_b32_e32 v189, 0xf149f2ca
	s_lshl_b32 s21, s44, 1
	s_waitcnt vmcnt(0) lgkmcnt(0)
	ds_write_b128 v66, v[28:31]
	ds_write_b128 v66, v[36:39] offset:13312
	ds_write_b128 v68, v[32:35] offset:26624
	ds_write_b128 v65, v[40:43] offset:23552
	ds_write_b128 v67, v[44:47] offset:128
	v_lshl_add_u64 v[28:29], s[10:11], 0, v[50:51]
	v_lshl_add_u64 v[32:33], v[28:29], 0, v[96:97]
	v_lshl_add_u64 v[28:29], s[10:11], 0, v[54:55]
	v_lshl_add_u64 v[40:41], v[28:29], 0, v[96:97]
	global_load_dwordx4 v[28:31], v[32:33], off
	s_nop 0
	global_load_dwordx4 v[32:35], v[32:33], off offset:128
	s_nop 0
	global_load_dwordx4 v[36:39], v[40:41], off
	s_nop 0
	global_load_dwordx4 v[40:43], v[40:41], off offset:128
	v_lshl_add_u64 v[44:45], s[8:9], 0, v[58:59]
	v_lshl_add_u64 v[44:45], v[44:45], 0, v[98:99]
	global_load_dwordx4 v[44:47], v[44:45], off
	s_movk_i32 s8, 0xa0
	v_mul_lo_u32 v184, v48, s8
	v_lshlrev_b32_e32 v97, 2, v62
	v_bfe_u32 v48, v60, 2, 2
	v_or_b32_e32 v48, v97, v48
	v_lshlrev_b32_e32 v50, 3, v63
	v_mul_u32_u24_e32 v187, 0xa0, v48
	v_lshlrev_b32_e32 v48, 3, v60
	s_lshl_b32 s8, s12, 9
	s_lshl_b32 s10, s18, 7
	v_add_u32_e32 v99, 0x3400, v95
	v_add_u32_e32 v185, 0x2800, v184
	v_and_b32_e32 v188, 24, v48
	s_ashr_i32 s9, s8, 31
	s_xor_b32 s20, s10, 0x900
	s_mov_b32 s10, 0
	v_lshlrev_b32_e32 v88, 1, v50
	v_lshlrev_b32_e32 v108, 1, v52
	v_mov_b32_e32 v81, 0xf149f2ca
	v_mov_b32_e32 v60, v0
	v_mov_b32_e32 v61, v0
	v_mov_b32_e32 v62, v0
	v_mov_b32_e32 v63, v0
	v_mov_b32_e32 v56, v0
	v_mov_b32_e32 v57, v0
	v_mov_b32_e32 v58, v0
	v_mov_b32_e32 v59, v0
	v_mov_b32_e32 v48, v0
	v_mov_b32_e32 v49, v0
	v_mov_b32_e32 v50, v0
	v_mov_b32_e32 v51, v0
	v_mov_b32_e32 v52, v0
	v_mov_b32_e32 v53, v0
	v_mov_b32_e32 v54, v0
	v_mov_b32_e32 v55, v0
	v_mov_b32_e32 v76, v0
	v_mov_b32_e32 v77, v0
	v_mov_b32_e32 v78, v0
	v_mov_b32_e32 v79, v0
	v_mov_b32_e32 v72, v0
	v_mov_b32_e32 v73, v0
	v_mov_b32_e32 v74, v0
	v_mov_b32_e32 v75, v0
	v_mov_b32_e32 v64, v0
	v_mov_b32_e32 v65, v0
	v_mov_b32_e32 v66, v0
	v_mov_b32_e32 v67, v0
	v_mov_b32_e32 v68, v0
	v_mov_b32_e32 v69, v0
	v_mov_b32_e32 v70, v0
	v_mov_b32_e32 v71, v0
	v_mov_b32_e32 v101, v100
	s_waitcnt lgkmcnt(0)
	s_barrier
	s_branch .LBB0_2968

.LBB0_2966:
	s_add_u32 s16, s16, s23
	s_addc_u32 s17, s17, 0
	s_add_u32 s23, s42, s12
	s_addc_u32 s24, s43, s13
	s_lshl_b64 s[12:13], s[16:17], 10
	s_add_u32 s12, s23, s12
	s_addc_u32 s13, s24, s13
	s_add_u32 s12, s12, s21
	s_addc_u32 s13, s13, 0
	s_add_u32 s23, s42, s10
	s_addc_u32 s24, s43, s11
	s_lshl_b64 s[10:11], s[16:17], 6
	s_waitcnt vmcnt(0)
	v_lshl_add_u64 v[28:29], v[102:103], 1, s[12:13]
	s_add_u32 s10, s23, s10
	v_lshl_add_u64 v[32:33], v[28:29], 0, v[88:89]
	v_lshl_add_u64 v[28:29], v[104:105], 1, s[12:13]
	s_addc_u32 s11, s24, s11
	v_lshl_add_u64 v[40:41], v[28:29], 0, v[88:89]
	global_load_dwordx4 v[28:31], v[32:33], off
	s_nop 0
	global_load_dwordx4 v[32:35], v[32:33], off offset:128
	s_nop 0
	global_load_dwordx4 v[36:39], v[40:41], off
	s_nop 0
	global_load_dwordx4 v[40:43], v[40:41], off offset:128
	v_lshl_add_u64 v[44:45], v[106:107], 1, s[10:11]
	v_mov_b32_e32 v109, v89
	v_lshl_add_u64 v[44:45], v[44:45], 0, v[108:109]
	global_load_dwordx4 v[44:47], v[44:45], off

.LBB0_2982:
	s_lshl_b32 s8, s16, 11
	s_add_i32 s10, s8, 0x1000
	s_lshl_b32 s11, s16, 8
	s_and_b64 s[8:9], s[18:19], exec
	s_cselect_b32 s20, s10, s11
	s_lshl_b32 s8, s6, 2
	s_lshl_b32 s6, s7, 5
	s_add_i32 s9, s6, 0x200
	s_and_b64 s[6:7], s[18:19], exec
	s_cselect_b32 s17, s87, 0x100
	s_cselect_b32 s8, s9, s8
	s_cmp_eq_u32 s31, 0
	v_ashrrev_i32_e32 v50, 3, v49
	s_cselect_b64 s[6:7], -1, 0
	s_ashr_i32 s9, s8, 31
	s_lshl_b64 s[22:23], s[8:9], 13
	s_waitcnt vmcnt(0)
	v_lshlrev_b32_e32 v44, 6, v50
	s_add_u32 s10, s79, s22
	v_ashrrev_i32_e32 v45, 31, v44
	s_addc_u32 s11, s80, s23
	v_lshlrev_b64 v[28:29], 1, v[44:45]
	v_lshl_add_u64 v[20:21], s[10:11], 0, v[28:29]
	s_add_u32 s10, s81, s22
	s_addc_u32 s11, s82, s23
	v_lshl_add_u64 v[22:23], s[10:11], 0, v[28:29]
	s_add_u32 s10, s83, s22
	v_xad_u32 v36, v50, -1, s17
	s_addc_u32 s11, s95, s23
	v_lshl_add_u64 v[28:29], s[10:11], 0, v[28:29]
	s_add_u32 s10, s85, s22
	v_lshlrev_b32_e32 v46, 3, v49
	v_cndmask_b32_e64 v36, v36, v50, s[6:7]
	s_addc_u32 s11, s88, s23
	v_ashrrev_i32_e32 v47, 31, v46
	s_ashr_i32 s21, s20, 31
	v_ashrrev_i32_e32 v37, 31, v36
	s_lshl_b32 s44, s29, 7
	s_lshl_b64 s[24:25], s[8:9], 8
	v_lshl_add_u64 v[32:33], v[46:47], 1, s[10:11]
	v_lshl_add_u64 v[36:37], v[36:37], 0, s[20:21]
	s_add_u32 s10, s89, s24
	v_lshlrev_b64 v[36:37], 9, v[36:37]
	s_addc_u32 s11, s46, s25
	s_lshl_b64 s[26:27], s[8:9], 2
	v_and_b32_e32 v51, 7, v49
	v_lshl_add_u64 v[36:37], s[50:51], 0, v[36:37]
	v_lshlrev_b32_e32 v64, 4, v49
	s_add_u32 s8, s47, s26
	v_lshlrev_b32_e32 v88, 4, v51
	v_lshl_add_u64 v[36:37], v[36:37], 0, s[44:45]
	v_and_b32_e32 v38, 0xf0, v64
	v_mov_b32_e32 v39, v89
	s_addc_u32 s9, s69, s27
	v_lshl_add_u64 v[20:21], v[20:21], 0, v[88:89]
	v_lshl_add_u64 v[24:25], v[22:23], 0, v[88:89]
	v_lshl_add_u64 v[28:29], v[28:29], 0, v[88:89]
	v_lshl_add_u64 v[36:37], v[36:37], 0, v[88:89]
	v_lshl_add_u64 v[40:41], s[10:11], 0, v[38:39]
	v_mov_b64_e32 v[52:53], s[8:9]
	s_barrier
	global_load_dwordx4 v[20:23], v[20:21], off
	s_nop 0
	global_load_dwordx4 v[24:27], v[24:25], off
	s_nop 0
	global_load_dwordx4 v[28:31], v[28:29], off
	s_nop 0
	global_load_dwordx4 v[32:35], v[32:33], off
	s_nop 0
	global_load_dwordx4 v[36:39], v[36:37], off
	s_nop 0
	global_load_dwordx4 v[40:43], v[40:41], off
	v_mul_lo_u32 v65, v50, s92
	global_load_dword v66, v[52:53], off
	v_add_u32_e32 v52, v65, v88
	v_cmp_gt_i32_e64 s[8:9], 16, v49
	s_waitcnt vmcnt(0) lgkmcnt(0)
	ds_write_b128 v52, v[20:23]
	ds_write_b128 v52, v[24:27] offset:18432
	ds_write_b128 v52, v[28:31] offset:27648
	ds_write_b128 v52, v[36:39] offset:9216
	ds_write_b128 v64, v[32:35] offset:36864
	s_and_saveexec_b64 s[10:11], s[8:9]
	ds_write_b128 v64, v[40:43] offset:45056
	s_or_b64 exec, exec, s[10:11]
	v_cmp_eq_u32_e64 s[10:11], 16, v49
	s_and_saveexec_b64 s[12:13], s[10:11]
	ds_write_b32 v89, v66 offset:45312
	s_or_b64 exec, exec, s[12:13]
	s_lshr_b32 s34, s30, 6
	s_lshl_b32 s37, s29, 6
	s_and_b64 s[12:13], s[6:7], exec
	s_mov_b32 s12, 0x6952000
	s_cselect_b32 s12, s12, 0x6f52000
	s_add_u32 s41, s42, s12
	s_addc_u32 s44, s43, 0
	s_ashr_i32 s70, s30, 8
	s_and_b64 s[12:13], s[18:19], exec
	s_cselect_b32 s36, 32, 4
	s_lshl_b32 s37, s37, 1
	v_lshlrev_b32_e32 v52, 3, v51
	s_add_u32 s12, s50, s37
	s_addc_u32 s13, s51, 0
	v_lshlrev_b32_e32 v52, 1, v52
	v_mov_b32_e32 v53, v89
	v_lshl_add_u64 v[52:53], s[12:13], 0, v[52:53]
	s_lshl_b32 s12, s40, 1
	s_add_i32 s13, s12, s70
	s_sub_i32 s12, s12, s70
	s_lshl_b32 s13, s13, 10
	s_lshl_b32 s12, s12, 6
	s_lshl_b32 s71, s70, 1
	s_add_i32 s72, s13, 0x16400
	s_add_i32 s12, s12, 64
	v_and_b32_e32 v56, 63, v49
	s_cmpk_lt_u32 s30, 0x100
	v_and_b32_e32 v67, 48, v49
	v_or_b32_e32 v49, s12, v56
	s_cselect_b64 s[12:13], -1, 0
	s_lshl_b32 s73, s70, 5
	s_add_u32 s37, s41, s37
	s_addc_u32 s41, s44, 0
	s_lshl_b32 s44, s40, 5
	s_add_u32 s64, s37, s44
	s_addc_u32 s65, s41, 0
	s_or_b32 s44, s71, 1
	v_lshlrev_b32_e32 v68, 3, v48
	v_lshlrev_b32_e32 v80, 4, v49
	v_lshlrev_b32_e32 v58, 2, v48
	v_lshlrev_b32_e32 v48, 1, v62
	v_mov_b32_e32 v49, v89
	s_lshl_b32 s37, s70, 10
	s_lshl_b32 s40, s40, 11
	s_lshl_b32 s41, s44, 9
	v_lshl_add_u64 v[54:55], s[64:65], 0, v[48:49]
	v_lshl_or_b32 v48, s44, 4, v62
	s_add_u32 s26, s26, 0xfc52004
	v_mul_lo_u32 v71, v48, s92
	v_sub_u32_e32 v48, s17, v58
	s_addc_u32 s27, s27, 0
	v_subrev_u32_e32 v48, s73, v48
	s_add_u32 s24, s24, 0xfbf2100
	v_or_b32_e32 v57, s73, v62
	v_subrev_u32_e32 v76, 17, v48
	s_addc_u32 s25, s25, 0
	v_lshlrev_b32_e32 v48, 4, v62
	v_lshlrev_b32_e32 v79, 4, v56
	v_lshlrev_b32_e32 v69, 3, v56
	v_mul_lo_u32 v70, v57, s92
	v_lshl_add_u64 v[56:57], s[24:25], 0, v[48:49]
	s_add_u32 s24, s22, 0x7b54000
	s_addc_u32 s25, s23, 0
	v_or_b32_e32 v73, s73, v58
	v_lshl_add_u64 v[58:59], v[46:47], 1, s[24:25]
	v_lshl_or_b32 v46, v51, 4, s22
	v_mov_b32_e32 v47, s23
	v_lshlrev_b32_e32 v74, 2, v73
	v_lshl_add_u64 v[60:61], v[44:45], 1, v[46:47]
	v_sub_u32_e32 v44, s17, v50
	s_mov_b32 s35, 0
	v_mul_u32_u24_e32 v72, 0x90, v62
	v_or_b32_e32 v75, 64, v74
	v_add_u32_e32 v77, 64, v50
	v_add_u32_e32 v78, 0xffffffbf, v44
	v_add_u32_e32 v79, s72, v79
	v_add_u32_e32 v80, 0x16400, v80
	s_mov_b32 s25, 0
	s_waitcnt lgkmcnt(0)
	s_barrier
	s_branch .LBB0_2989

.LBB0_2989:
	s_add_i32 s24, s25, 1
	s_cmp_lt_u32 s24, s36
	s_cselect_b64 s[22:23], -1, 0
	s_cmp_ge_u32 s24, s36
	s_cbranch_scc1 .LBB0_2991
	s_waitcnt vmcnt(0)
	v_lshl_add_u64 v[28:29], s[42:43], 0, v[60:61]
	v_add_co_u32_e32 v20, vcc, 0x8754000, v28
	v_add_u32_e32 v36, s35, v77
	s_nop 0
	v_addc_co_u32_e32 v21, vcc, 0, v29, vcc
	v_cndmask_b32_e64 v36, v78, v36, s[6:7]
	v_add_co_u32_e32 v24, vcc, 0xe3f4000, v28
	v_ashrrev_i32_e32 v37, 31, v36
	s_nop 0
	v_addc_co_u32_e32 v25, vcc, 0, v29, vcc
	v_lshl_add_u64 v[36:37], v[36:37], 0, s[20:21]
	s_add_u32 s64, s42, s26
	v_add_co_u32_e32 v28, vcc, 0xeff4000, v28
	v_lshlrev_b64 v[36:37], 9, v[36:37]
	s_addc_u32 s65, s43, s27
	v_addc_co_u32_e32 v29, vcc, 0, v29, vcc
	v_lshl_add_u64 v[32:33], s[42:43], 0, v[58:59]
	v_lshl_add_u64 v[36:37], v[52:53], 0, v[36:37]
	v_lshl_add_u64 v[40:41], s[42:43], 0, v[56:57]
	v_mov_b64_e32 v[44:45], s[64:65]
	global_load_dwordx4 v[20:23], v[20:21], off
	s_nop 0
	global_load_dwordx4 v[24:27], v[24:25], off
	s_nop 0
	global_load_dwordx4 v[28:31], v[28:29], off
	s_nop 0
	global_load_dwordx4 v[32:35], v[32:33], off
	s_nop 0
	global_load_dwordx4 v[36:39], v[36:37], off
	s_nop 0
	global_load_dwordx4 v[40:43], v[40:41], off
	s_nop 0
	global_load_dword v66, v[44:45], off

.Lqe6:
	s_add_i32 s8, s10, s65
	s_min_i32 s6, s8, 0x80
	s_lshl_b32 s6, s6, 8
	s_and_b32 s12, s6, 0x700
	s_min_u32 s6, s12, 0x680
	s_add_i32 s9, s8, 0xffffff80
	s_add_i32 s11, s6, 0x180
	s_cmpk_lt_i32 s8, 0x80
	s_cselect_b64 s[6:7], -1, 0
	s_and_b64 s[6:7], s[6:7], exec
	v_sub_u32_e64 v4, s12, v180 clamp
	s_cselect_b32 s6, s8, s9
	s_cselect_b32 s7, 5, 2
	v_readfirstlane_b32 s9, v4
	s_cselect_b32 s13, s9, 0
	s_cselect_b32 s9, s11, 0x100
	s_ashr_i32 s14, s6, s7
	s_lshl_b32 s6, s14, 11
	s_add_i32 s11, s6, 0x1000
	s_lshl_b32 s15, s14, 8
	s_cmpk_lt_i32 s8, 0x80
	s_cselect_b64 s[6:7], -1, 0
	s_and_b64 s[6:7], s[6:7], exec
	s_cselect_b32 s15, s11, s15
	s_lshr_b32 s11, s10, 3
	s_cmpk_lt_i32 s8, 0x80
	s_cselect_b64 s[70:71], -1, 0
	s_waitcnt vmcnt(0)
	v_mov_b32_e32 v20, v175
	s_and_b64 s[6:7], s[70:71], exec
	s_cselect_b32 s6, s11, s10
	v_ashrrev_i32_e32 v4, 1, v20
	s_and_b32 s17, s6, 3
	v_and_b32_e32 v40, 0xffffffe0, v4
	v_and_b32_e32 v38, 15, v20
	v_add_u32_e32 v4, s12, v40
	s_lshl_b32 s6, s17, 7
	v_bfe_u32 v39, v20, 4, 2
	v_or_b32_e32 v4, v4, v38
	s_add_u32 s6, s54, s6
	v_add_u32_e32 v92, s15, v4
	s_addc_u32 s7, s57, 0
	v_lshlrev_b32_e32 v94, 4, v39
	v_mov_b32_e32 v95, v89
	v_lshl_add_u64 v[12:13], s[6:7], 0, v[94:95]
	v_ashrrev_i32_e32 v93, 31, v92
	s_mov_b64 s[6:7], s[0:1]
	v_lshlrev_b64 v[4:5], 9, v[92:93]
	s_add_u32 s6, s6, s3
	v_lshl_add_u64 v[8:9], v[12:13], 0, v[4:5]
	s_addc_u32 s7, s7, s63
	global_load_dwordx4 v[4:7], v[8:9], off
	s_nop 0
	global_load_dwordx4 v[8:11], v[8:9], off offset:64
	s_load_dwordx2 s[6:7], s[6:7], 0x98
	v_or_b32_e32 v90, 16, v92
	v_ashrrev_i32_e32 v91, 31, v90
	v_lshlrev_b64 v[14:15], 9, v[90:91]
	s_lshl_b32 s8, s17, 2
	v_lshl_add_u64 v[16:17], v[12:13], 0, v[14:15]
	v_mov_b32_e32 v21, s8
	global_load_dwordx4 v[12:15], v[16:17], off
	s_nop 0
	global_load_dwordx4 v[16:19], v[16:17], off offset:64
	s_sub_i32 s16, s9, s13
	s_waitcnt lgkmcnt(0)
	global_load_dword v41, v21, s[6:7] offset:16
	s_ashr_i32 s76, s16, 7
	s_cmp_lt_i32 s76, 1
	s_mov_b64 s[8:9], -1
	s_barrier
	s_cbranch_scc0 .LBB0_3044
	s_lshl_b32 s6, s14, 9
	s_ashr_i32 s7, s6, 31
	s_sub_i32 s8, 0, s16
	s_add_u32 s6, s6, s8
	s_addc_u32 s7, s7, 0
	s_add_u32 s6, s6, 0x800
	s_addc_u32 s7, s7, 0
	s_mov_b64 s[8:9], 0

.LBB0_3047:
	s_and_b64 s[18:19], s[70:71], exec
	s_cselect_b32 s18, 4, 0
	s_add_i32 s44, s76, s18
	s_add_u32 s10, s42, s10
	s_addc_u32 s11, s43, s11
	s_lshl_b64 s[6:7], s[6:7], 8
	s_add_u32 s10, s10, s6
	s_addc_u32 s11, s11, s7
	s_lshl_b32 s18, s17, 5
	s_and_b32 s18, s18, 64
	s_lshl_b32 s77, s18, 1
	s_add_u32 s10, s10, s77
	s_addc_u32 s11, s11, 0
	s_add_u32 s8, s42, s8
	s_addc_u32 s9, s43, s9
	s_add_u32 s6, s8, s6
	v_ashrrev_i32_e32 v36, 3, v20
	s_addc_u32 s7, s9, s7
	v_ashrrev_i32_e32 v37, 31, v36
	v_add_u32_e32 v42, 64, v36
	s_add_u32 s6, s6, s77
	v_lshlrev_b64 v[28:29], 8, v[36:37]
	v_and_b32_e32 v44, 7, v20
	v_ashrrev_i32_e32 v43, 31, v42
	s_addc_u32 s7, s7, 0
	v_lshl_add_u64 v[22:23], s[10:11], 0, v[28:29]
	v_lshlrev_b32_e32 v98, 4, v44
	v_mov_b32_e32 v99, v89
	v_lshlrev_b64 v[30:31], 8, v[42:43]
	v_lshl_add_u64 v[20:21], v[22:23], 0, v[98:99]
	v_lshl_add_u64 v[22:23], s[10:11], 0, v[30:31]
	v_lshl_add_u64 v[28:29], s[6:7], 0, v[28:29]
	v_lshl_add_u64 v[30:31], s[6:7], 0, v[30:31]
	v_lshl_add_u64 v[24:25], v[22:23], 0, v[98:99]
	v_lshl_add_u64 v[28:29], v[28:29], 0, v[98:99]
	v_lshl_add_u64 v[32:33], v[30:31], 0, v[98:99]
	global_load_dwordx4 v[20:23], v[20:21], off
	s_nop 0
	global_load_dwordx4 v[24:27], v[24:25], off
	s_nop 0
	global_load_dwordx4 v[28:31], v[28:29], off
	s_nop 0
	global_load_dwordx4 v[32:35], v[32:33], off
	v_mul_lo_u32 v99, v36, s92
	v_lshlrev_b32_e32 v95, 3, v44
	v_lshlrev_b64 v[100:101], 7, v[36:37]
	v_add_u32_e32 v37, v99, v98
	v_lshlrev_b32_e32 v44, 4, v42
	v_lshlrev_b64 v[102:103], 7, v[42:43]
	s_movk_i32 s6, 0x2400
	s_cmp_lt_i32 s44, 2
	v_lshl_add_u32 v42, v36, 4, v37
	v_add3_u32 v43, v37, s6, v44
	s_waitcnt vmcnt(0) lgkmcnt(0)
	ds_write_b128 v37, v[20:23]
	ds_write_b128 v37, v[24:27] offset:9216
	ds_write_b128 v42, v[28:31] offset:18432
	ds_write_b128 v43, v[32:35] offset:18432
	s_cbranch_scc1 .LBB0_3054
	s_cmp_lt_i32 s76, 2
	s_mov_b64 s[8:9], -1
	s_cbranch_scc0 .LBB0_3050
	s_lshl_b32 s6, s14, 9
	s_ashr_i32 s7, s6, 31
	s_sub_i32 s8, 0x80, s16
	s_add_u32 s6, s6, s8
	s_addc_u32 s7, s7, 0
	s_add_u32 s6, s6, 0x800
	s_addc_u32 s7, s7, 0
	s_mov_b64 s[8:9], 0

.LBB0_3053:
	s_add_u32 s10, s42, s10
	s_addc_u32 s11, s43, s11
	s_lshl_b64 s[6:7], s[6:7], 8
	s_add_u32 s10, s10, s6
	s_addc_u32 s11, s11, s7
	s_add_u32 s10, s10, s77
	s_addc_u32 s11, s11, 0
	s_add_u32 s8, s42, s8
	s_addc_u32 s9, s43, s9
	s_add_u32 s6, s8, s6
	s_addc_u32 s7, s9, s7
	s_add_u32 s6, s6, s77
	s_addc_u32 s7, s7, 0
	v_lshlrev_b64 v[28:29], 1, v[100:101]
	v_lshlrev_b64 v[30:31], 1, v[102:103]
	v_lshl_add_u64 v[20:21], s[10:11], 0, v[28:29]
	v_lshlrev_b32_e32 v88, 1, v95
	v_lshl_add_u64 v[22:23], s[10:11], 0, v[30:31]
	v_lshl_add_u64 v[28:29], s[6:7], 0, v[28:29]
	v_lshl_add_u64 v[30:31], s[6:7], 0, v[30:31]
	v_lshl_add_u64 v[20:21], v[20:21], 0, v[88:89]
	v_lshl_add_u64 v[24:25], v[22:23], 0, v[88:89]
	v_lshl_add_u64 v[28:29], v[28:29], 0, v[88:89]
	v_lshl_add_u64 v[32:33], v[30:31], 0, v[88:89]
	global_load_dwordx4 v[20:23], v[20:21], off
	s_nop 0
	global_load_dwordx4 v[24:27], v[24:25], off
	s_nop 0
	global_load_dwordx4 v[28:31], v[28:29], off
	s_nop 0
	global_load_dwordx4 v[32:35], v[32:33], off

.LBB0_3064:
	s_add_u32 s10, s42, s10
	s_addc_u32 s11, s43, s11
	s_lshl_b64 s[8:9], s[8:9], 8
	s_add_u32 s10, s10, s8
	s_addc_u32 s11, s11, s9
	s_add_u32 s10, s10, s77
	s_addc_u32 s11, s11, 0
	s_add_u32 s6, s42, s6
	s_addc_u32 s7, s43, s7
	s_add_u32 s6, s6, s8
	s_addc_u32 s7, s7, s9
	s_add_u32 s6, s6, s77
	s_addc_u32 s7, s7, 0
	s_waitcnt vmcnt(0)
	v_lshlrev_b64 v[28:29], 1, v[100:101]
	v_lshlrev_b64 v[30:31], 1, v[102:103]
	v_lshl_add_u64 v[20:21], s[10:11], 0, v[28:29]
	v_lshlrev_b32_e32 v88, 1, v95
	v_lshl_add_u64 v[22:23], s[10:11], 0, v[30:31]
	v_lshl_add_u64 v[28:29], s[6:7], 0, v[28:29]
	v_lshl_add_u64 v[30:31], s[6:7], 0, v[30:31]
	v_lshl_add_u64 v[20:21], v[20:21], 0, v[88:89]
	v_lshl_add_u64 v[24:25], v[22:23], 0, v[88:89]
	v_lshl_add_u64 v[28:29], v[28:29], 0, v[88:89]
	v_lshl_add_u64 v[32:33], v[30:31], 0, v[88:89]
	global_load_dwordx4 v[20:23], v[20:21], off
	s_nop 0
	global_load_dwordx4 v[24:27], v[24:25], off
	s_nop 0
	global_load_dwordx4 v[28:31], v[28:29], off
	s_nop 0
	global_load_dwordx4 v[32:35], v[32:33], off

.Lhy_ctx1_done:
	s_and_b64 s[18:19], s[6:7], exec
	s_cselect_b32 s44, s2, 0xddf2000
	v_lshl_add_u64 v[20:21], v[12:13], 0, s[44:45]
	v_lshl_add_u64 v[18:19], s[8:9], 1, v[20:21]
	global_load_dwordx2 v[32:33], v[18:19], off
	v_cndmask_b32_e64 v18, v23, v22, s[6:7]
	s_lshl_b32 s6, s14, 1
	s_add_i32 s6, s16, s6
	v_mov_b32_e32 v34, v8
	v_lshl_add_u32 v8, v25, 1, s6
	ds_read_b64 v[36:37], v8 offset:512
	v_mov_b32_e32 v35, v10
	v_mov_b32_e32 v10, v9
	s_mov_b64 s[6:7], -1
	s_and_b64 vcc, exec, s[12:13]
	s_waitcnt lgkmcnt(0)
	v_lshlrev_b32_e32 v9, 16, v37
	v_lshlrev_b32_e32 v8, 16, v36
	v_and_b32_e32 v37, 0xffff0000, v37
	v_and_b32_e32 v36, 0xffff0000, v36
	v_pk_fma_f32 v[8:9], v[18:19], v[8:9], v[34:35] op_sel_hi:[0,1,1]
	v_pk_fma_f32 v[10:11], v[18:19], v[36:37], v[10:11] op_sel_hi:[0,1,1]
	s_waitcnt vmcnt(0)
	v_lshlrev_b32_e32 v35, 16, v33
	v_lshlrev_b32_e32 v34, 16, v32
	v_and_b32_e32 v33, 0xffff0000, v33
	v_and_b32_e32 v32, 0xffff0000, v32
	v_pk_mul_f32 v[10:11], v[10:11], v[32:33]
	v_pk_mul_f32 v[8:9], v[8:9], v[34:35]
	v_and_b32_sdwa v32, v11, v176 dst_sel:DWORD dst_unused:UNUSED_PAD src0_sel:WORD_1 src1_sel:DWORD
	v_and_b32_sdwa v33, v10, v176 dst_sel:DWORD dst_unused:UNUSED_PAD src0_sel:WORD_1 src1_sel:DWORD
	v_and_b32_sdwa v19, v9, v176 dst_sel:DWORD dst_unused:UNUSED_PAD src0_sel:WORD_1 src1_sel:DWORD
	v_and_b32_sdwa v31, v8, v176 dst_sel:DWORD dst_unused:UNUSED_PAD src0_sel:WORD_1 src1_sel:DWORD
	v_add3_u32 v11, v11, v32, s93
	v_add3_u32 v10, v10, v33, s93
	v_add3_u32 v8, v8, v31, s93
	v_add3_u32 v9, v9, v19, s93
	v_and_b32_e32 v11, 0xffff0000, v11
	v_and_b32_e32 v10, 0xffff0000, v10
	v_or_b32_sdwa v9, v11, v9 dst_sel:DWORD dst_unused:UNUSED_PAD src0_sel:DWORD src1_sel:WORD_1
	v_or_b32_sdwa v8, v10, v8 dst_sel:DWORD dst_unused:UNUSED_PAD src0_sel:DWORD src1_sel:WORD_1
	s_cbranch_vccz .LBB0_3096
	flat_store_dwordx2 v[14:15], v[8:9]
	s_mov_b64 s[6:7], 0

.LBB0_3098:
	v_lshl_add_u64 v[8:9], s[10:11], 1, v[20:21]
	global_load_dwordx2 v[8:9], v[8:9], off
	s_lshl_b32 s6, s15, 1
	s_add_i32 s16, s16, s6
	v_mov_b32_e32 v10, v4
	v_lshl_add_u32 v4, v25, 1, s16
	ds_read_b64 v[20:21], v4 offset:512
	v_cndmask_b32_e64 v4, 0, 1, s[12:13]
	v_mov_b32_e32 v19, v18
	v_mov_b32_e32 v11, v6
	v_mov_b32_e32 v6, v5
	v_cmp_ne_u32_e64 s[6:7], 1, v4
	s_waitcnt lgkmcnt(0)
	v_lshlrev_b32_e32 v5, 16, v21
	v_lshlrev_b32_e32 v4, 16, v20
	v_and_b32_e32 v21, 0xffff0000, v21
	v_and_b32_e32 v20, 0xffff0000, v20
	v_pk_fma_f32 v[4:5], v[18:19], v[4:5], v[10:11]
	v_pk_fma_f32 v[6:7], v[18:19], v[20:21], v[6:7]
	s_andn2_b64 vcc, exec, s[12:13]
	s_mov_b64 s[12:13], -1
	s_waitcnt vmcnt(0)
	v_lshlrev_b32_e32 v11, 16, v9
	v_lshlrev_b32_e32 v10, 16, v8
	v_and_b32_e32 v9, 0xffff0000, v9
	v_and_b32_e32 v8, 0xffff0000, v8
	v_pk_mul_f32 v[6:7], v[6:7], v[8:9]
	v_pk_mul_f32 v[4:5], v[4:5], v[10:11]
	v_and_b32_sdwa v10, v7, v176 dst_sel:DWORD dst_unused:UNUSED_PAD src0_sel:WORD_1 src1_sel:DWORD
	v_and_b32_sdwa v11, v6, v176 dst_sel:DWORD dst_unused:UNUSED_PAD src0_sel:WORD_1 src1_sel:DWORD
	v_and_b32_sdwa v8, v5, v176 dst_sel:DWORD dst_unused:UNUSED_PAD src0_sel:WORD_1 src1_sel:DWORD
	v_and_b32_sdwa v9, v4, v176 dst_sel:DWORD dst_unused:UNUSED_PAD src0_sel:WORD_1 src1_sel:DWORD
	v_add3_u32 v7, v7, v10, s93
	v_add3_u32 v6, v6, v11, s93
	v_add3_u32 v4, v4, v9, s93
	v_add3_u32 v5, v5, v8, s93
	v_and_b32_e32 v7, 0xffff0000, v7
	v_and_b32_e32 v6, 0xffff0000, v6
	v_or_b32_sdwa v5, v7, v5 dst_sel:DWORD dst_unused:UNUSED_PAD src0_sel:DWORD src1_sel:WORD_1
	v_or_b32_sdwa v4, v6, v4 dst_sel:DWORD dst_unused:UNUSED_PAD src0_sel:DWORD src1_sel:WORD_1
	s_cbranch_vccnz .LBB0_3100
	s_mov_b64 s[12:13], 0
	flat_store_dwordx2 v[16:17], v[4:5]
